# conv-tile staging loads issued together; tconv-with-gain and compress-bias loops: loads no longer serialized behind per-load waits
# speedup vs baseline: 1.1177x; 1.0083x over previous
; DEVI void tconv(const float* __restrict__ src, int K, int N, u16* __restrict__ dst, int Npad, int ldd,
;                 const float* __restrict__ gain, int gtid, int gsz) {
;     ...
;     for (int j = 0; j < 8; ++j) {
;       float v = 0.f;
;       if (n < N) {
;         v = src[(size_t)(kc * 8 + j) * N + n];
;         if (gain) v *= gain[kc * 8 + j];
;       }
;       f[j] = v;
.LBB0_64:
	v_ashrrev_i32_e32 v2, 31, v11
	v_lshrrev_b32_e32 v2, 22, v2
	v_add_u32_e32 v2, v11, v2
	s_load_dwordx16 s[16:31], s[68:69], 0x80
	v_ashrrev_i32_e32 v3, 10, v2
	v_mul_i32_i24_e32 v2, 0x400, v3
	v_sub_u32_e32 v2, v11, v2
	v_lshlrev_b32_e32 v4, 3, v3
	v_ashrrev_i32_e32 v3, 31, v2
	v_ashrrev_i32_e32 v5, 31, v4
	s_waitcnt lgkmcnt(0)
	v_lshl_add_u64 v[6:7], v[2:3], 2, s[18:19]
	v_lshlrev_b64 v[8:9], 12, v[4:5]
	v_lshl_add_u64 v[8:9], v[6:7], 0, v[8:9]
	global_load_dword v3, v[8:9], off
	s_load_dwordx16 s[16:31], s[68:69], 0x40
	s_and_b64 vcc, exec, s[8:9]
	s_waitcnt lgkmcnt(0)
	v_lshl_add_u64 v[8:9], v[4:5], 2, s[30:31]
	s_cbranch_vccnz .LBB0_66
	global_load_dwordx4 v[234:237], v[8:9], off
	global_load_dwordx4 v[238:241], v[8:9], off offset:16
	v_or_b32_e32 v12, 1, v4
	v_ashrrev_i32_e32 v13, 31, v12
	v_lshlrev_b64 v[12:13], 12, v[12:13]
	v_lshl_add_u64 v[12:13], v[6:7], 0, v[12:13]
	global_load_dword v12, v[12:13], off
	v_or_b32_e32 v14, 2, v4
	v_ashrrev_i32_e32 v15, 31, v14
	v_lshlrev_b64 v[14:15], 12, v[14:15]
	v_lshl_add_u64 v[14:15], v[6:7], 0, v[14:15]
	global_load_dword v13, v[14:15], off
	v_or_b32_e32 v14, 3, v4
	v_ashrrev_i32_e32 v15, 31, v14
	v_lshlrev_b64 v[14:15], 12, v[14:15]
	v_lshl_add_u64 v[14:15], v[6:7], 0, v[14:15]
	global_load_dword v14, v[14:15], off
	v_or_b32_e32 v16, 4, v4
	v_ashrrev_i32_e32 v17, 31, v16
	v_lshlrev_b64 v[16:17], 12, v[16:17]
	v_lshl_add_u64 v[16:17], v[6:7], 0, v[16:17]
	global_load_dword v15, v[16:17], off
	v_or_b32_e32 v16, 5, v4
	v_ashrrev_i32_e32 v17, 31, v16
	v_lshlrev_b64 v[16:17], 12, v[16:17]
	v_lshl_add_u64 v[16:17], v[6:7], 0, v[16:17]
	global_load_dword v16, v[16:17], off
	v_or_b32_e32 v24, 6, v4
	v_ashrrev_i32_e32 v25, 31, v24
	v_lshlrev_b64 v[24:25], 12, v[24:25]
	v_lshl_add_u64 v[24:25], v[6:7], 0, v[24:25]
	global_load_dword v17, v[24:25], off
	v_or_b32_e32 v24, 7, v4
	v_ashrrev_i32_e32 v25, 31, v24
	v_lshlrev_b64 v[24:25], 12, v[24:25]
	v_lshl_add_u64 v[6:7], v[6:7], 0, v[24:25]
	global_load_dword v6, v[6:7], off
	s_waitcnt vmcnt(0)
	v_mul_f32_e32 v3, v3, v234
	v_mul_f32_e32 v12, v12, v235
	v_mul_f32_e32 v13, v13, v236
	v_mul_f32_e32 v14, v14, v237
	v_mul_f32_e32 v15, v15, v238
	v_mul_f32_e32 v16, v16, v239
	v_mul_f32_e32 v17, v17, v240
	v_mul_f32_e32 v6, v6, v241
	s_branch .LBB0_63

; DEVI void tconv(const float* __restrict__ src, int K, int N, u16* __restrict__ dst, int Npad, int ldd,
;                 const float* __restrict__ gain, int gtid, int gsz) {
;     ...
;     for (int j = 0; j < 8; ++j) {
;       float v = 0.f;
;       if (n < N) {
;         v = src[(size_t)(kc * 8 + j) * N + n];
;         if (gain) v *= gain[kc * 8 + j];
;       }
;       f[j] = v;
.LBB0_93:
	v_ashrrev_i32_e32 v2, 31, v11
	v_lshrrev_b32_e32 v2, 21, v2
	s_load_dwordx16 s[16:31], s[68:69], 0x80
	v_add_u32_e32 v2, v11, v2
	v_ashrrev_i32_e32 v3, 11, v2
	v_mul_i32_i24_e32 v2, 0x800, v3
	v_sub_u32_e32 v2, v11, v2
	v_lshlrev_b32_e32 v4, 3, v3
	v_ashrrev_i32_e32 v3, 31, v2
	s_waitcnt lgkmcnt(0)
	s_mov_b64 s[20:21], s[28:29]
	v_ashrrev_i32_e32 v5, 31, v4
	v_lshl_add_u64 v[6:7], v[2:3], 2, s[20:21]
	v_lshlrev_b64 v[8:9], 13, v[4:5]
	v_lshl_add_u64 v[8:9], v[6:7], 0, v[8:9]
	global_load_dword v3, v[8:9], off
	s_mov_b64 s[18:19], s[26:27]
	s_and_b64 vcc, exec, s[4:5]
	v_lshl_add_u64 v[8:9], v[4:5], 2, s[18:19]
	s_mov_b64 s[22:23], s[30:31]
	s_cbranch_vccnz .LBB0_95
	global_load_dwordx4 v[234:237], v[8:9], off
	global_load_dwordx4 v[238:241], v[8:9], off offset:16
	v_or_b32_e32 v12, 1, v4
	v_ashrrev_i32_e32 v13, 31, v12
	v_lshlrev_b64 v[12:13], 13, v[12:13]
	v_lshl_add_u64 v[12:13], v[6:7], 0, v[12:13]
	global_load_dword v12, v[12:13], off
	v_or_b32_e32 v14, 2, v4
	v_ashrrev_i32_e32 v15, 31, v14
	v_lshlrev_b64 v[14:15], 13, v[14:15]
	v_lshl_add_u64 v[14:15], v[6:7], 0, v[14:15]
	global_load_dword v13, v[14:15], off
	v_or_b32_e32 v14, 3, v4
	v_ashrrev_i32_e32 v15, 31, v14
	v_lshlrev_b64 v[14:15], 13, v[14:15]
	v_lshl_add_u64 v[14:15], v[6:7], 0, v[14:15]
	global_load_dword v14, v[14:15], off
	v_or_b32_e32 v16, 4, v4
	v_ashrrev_i32_e32 v17, 31, v16
	v_lshlrev_b64 v[16:17], 13, v[16:17]
	v_lshl_add_u64 v[16:17], v[6:7], 0, v[16:17]
	global_load_dword v15, v[16:17], off
	v_or_b32_e32 v16, 5, v4
	v_ashrrev_i32_e32 v17, 31, v16
	v_lshlrev_b64 v[16:17], 13, v[16:17]
	v_lshl_add_u64 v[16:17], v[6:7], 0, v[16:17]
	global_load_dword v16, v[16:17], off
	v_or_b32_e32 v24, 6, v4
	v_ashrrev_i32_e32 v25, 31, v24
	v_lshlrev_b64 v[24:25], 13, v[24:25]
	v_lshl_add_u64 v[24:25], v[6:7], 0, v[24:25]
	global_load_dword v17, v[24:25], off
	v_or_b32_e32 v24, 7, v4
	v_ashrrev_i32_e32 v25, 31, v24
	v_lshlrev_b64 v[24:25], 13, v[24:25]
	v_lshl_add_u64 v[6:7], v[6:7], 0, v[24:25]
	global_load_dword v6, v[6:7], off
	s_waitcnt vmcnt(0)
	v_mul_f32_e32 v3, v3, v234
	v_mul_f32_e32 v12, v12, v235
	v_mul_f32_e32 v13, v13, v236
	v_mul_f32_e32 v14, v14, v237
	v_mul_f32_e32 v15, v15, v238
	v_mul_f32_e32 v16, v16, v239
	v_mul_f32_e32 v17, v17, v240
	v_mul_f32_e32 v6, v6, v241
	s_branch .LBB0_92

; DEVI void phase0(const Params& p) {
;     ...
;   for (int o = gw; o < 256; o += nw) {
;     const int ty = o >> 7, n = o & 127;
;     float s = 0.f;
; #pragma unroll 8
;     for (int k = lane; k < 2048; k += 64)
;       s += p.cmp_pos[ty * 2048 + k] * p.cmp_w1[((size_t)ty * 2048 + k) * 128 + n];
;     s = wave_sum(s);
;     if (lane == 0) p.biasp[o] = s + p.cmp_b1[o];
;   }
.LBB0_185:
	global_load_dword v100, v[4:5], off offset:-1792
	global_load_dword v101, v[4:5], off offset:-1536
	global_load_dword v102, v[4:5], off offset:-1280
	global_load_dword v103, v[4:5], off offset:-1024
	global_load_dword v104, v[4:5], off offset:-768
	global_load_dword v105, v[4:5], off offset:-512
	global_load_dword v106, v[4:5], off offset:-256
	global_load_dword v107, v[4:5], off
	v_add_co_u32_e32 v16, vcc, 0xfffc8000, v2
	s_nop 1
	v_addc_co_u32_e32 v17, vcc, -1, v3, vcc
	global_load_dword v108, v[16:17], off
	v_add_co_u32_e32 v16, vcc, 0xfffd0000, v2
	s_nop 1
	v_addc_co_u32_e32 v17, vcc, -1, v3, vcc
	global_load_dword v109, v[16:17], off
	v_add_co_u32_e32 v16, vcc, 0xfffd8000, v2
	s_nop 1
	v_addc_co_u32_e32 v17, vcc, -1, v3, vcc
	global_load_dword v110, v[16:17], off
	v_add_co_u32_e32 v16, vcc, 0xfffe0000, v2
	s_nop 1
	v_addc_co_u32_e32 v17, vcc, -1, v3, vcc
	global_load_dword v111, v[16:17], off
	v_add_co_u32_e32 v16, vcc, 0xfffe8000, v2
	s_nop 1
	v_addc_co_u32_e32 v17, vcc, -1, v3, vcc
	global_load_dword v112, v[16:17], off
	v_add_co_u32_e32 v16, vcc, 0xffff0000, v2
	s_nop 1
	v_addc_co_u32_e32 v17, vcc, -1, v3, vcc
	global_load_dword v113, v[16:17], off
	v_add_co_u32_e32 v16, vcc, 0xffff8000, v2
	s_nop 1
	v_addc_co_u32_e32 v17, vcc, -1, v3, vcc
	global_load_dword v114, v[16:17], off
	global_load_dword v115, v[2:3], off
	s_mov_b64 s[18:19], 0x40000
	v_add_u32_e32 v15, 0x200, v15
	v_lshl_add_u64 v[2:3], v[2:3], 0, s[18:19]
	s_mov_b64 s[18:19], 0x800
	v_lshl_add_u64 v[4:5], v[4:5], 0, s[18:19]
	s_movk_i32 s18, 0x5ff
	v_cmp_lt_u32_e32 vcc, s18, v15
	s_or_b64 s[10:11], vcc, s[10:11]
	s_waitcnt vmcnt(0)
	v_fmac_f32_e32 v14, v100, v108
	v_fmac_f32_e32 v14, v101, v109
	v_fmac_f32_e32 v14, v102, v110
	v_fmac_f32_e32 v14, v103, v111
	v_fmac_f32_e32 v14, v104, v112
	v_fmac_f32_e32 v14, v105, v113
	v_fmac_f32_e32 v14, v106, v114
	v_fmac_f32_e32 v14, v107, v115
	s_andn2_b64 exec, exec, s[10:11]
	s_cbranch_execnz .LBB0_185
	s_or_b64 exec, exec, s[10:11]
	ds_bpermute_b32 v2, v7, v14
	s_waitcnt lgkmcnt(0)
	v_add_f32_e32 v2, v14, v2
	ds_bpermute_b32 v3, v8, v2
	s_waitcnt lgkmcnt(0)
	v_add_f32_e32 v2, v2, v3
	ds_bpermute_b32 v3, v9, v2
	s_waitcnt lgkmcnt(0)
	v_add_f32_e32 v2, v2, v3
	ds_bpermute_b32 v3, v10, v2
	s_waitcnt lgkmcnt(0)
	v_add_f32_e32 v2, v2, v3
	ds_bpermute_b32 v3, v11, v2
	s_waitcnt lgkmcnt(0)
	v_add_f32_e32 v2, v2, v3
	ds_bpermute_b32 v3, v12, v2
	s_and_saveexec_b64 s[10:11], s[6:7]
	s_cbranch_execz .LBB0_183
	s_load_dwordx16 s[72:87], s[68:69], 0x40
	v_ashrrev_i32_e32 v23, 31, v22
	v_lshlrev_b64 v[4:5], 2, v[22:23]
	s_waitcnt lgkmcnt(0)
	v_add_f32_e32 v2, v2, v3
	v_lshl_add_u64 v[14:15], s[78:79], 0, v[4:5]
	global_load_dword v14, v[14:15], off
	s_load_dwordx16 s[72:87], s[68:69], 0x140
	s_waitcnt lgkmcnt(0)
	v_lshl_add_u64 v[4:5], s[86:87], 0, v[4:5]
	s_waitcnt vmcnt(0)
	v_add_f32_e32 v2, v2, v14
	global_store_dword v[4:5], v2, off
	s_branch .LBB0_183

; DEVI unsigned pack2(float a, float b) { return (unsigned)f2bf(a) | ((unsigned)f2bf(b) << 16); }
; DEVI float sigmoidf_(float x) { return __builtin_amdgcn_rcpf(1.f + __expf(-x)); }
; DEVI void conv_tile(const Params& p, unsigned char* smem, int ct) {
;     ...
;   for (int it = tid; it < 62 * 64; it += 256) {
;     const int r = it >> 6, c8 = it & 63;
;     const int t = t0 - 30 + r;
;     uint4 pk = {0u, 0u, 0u, 0u};
;     if (t >= 0) {
;       const u16* src = p.proj + ((size_t)b * T + t) * LDP + c8 * 8;
;       const uint4 a = *(const uint4*)src, bb = *(const uint4*)(src + 512);
;       const unsigned au[4] = {a.x, a.y, a.z, a.w}, bu[4] = {bb.x, bb.y, bb.z, bb.w};
;       unsigned o[4];
; #pragma unroll
;       for (int j = 0; j < 4; ++j) {
;         const float a0 = __uint_as_float(au[j] << 16), a1 = __uint_as_float(au[j] & 0xffff0000u);
;         const float b0 = __uint_as_float(bu[j] << 16), b1 = __uint_as_float(bu[j] & 0xffff0000u);
;         o[j] = pack2(a0 * sigmoidf_(b0), a1 * sigmoidf_(b1));
;       }
;       pk.x = o[0]; pk.y = o[1]; pk.z = o[2]; pk.w = o[3];
;     }
;     *(uint4*)(sU + r * 512 + c8 * 8) = pk;
;   }
.LBB0_558:
	v_ashrrev_i32_e32 v7, 6, v6
	v_add_u32_e32 v8, s23, v7
	v_cmp_lt_i32_e32 vcc, -1, v8
	v_mov_b32_e32 v0, 0
	v_mov_b32_e32 v1, 0
	v_mov_b32_e32 v2, 0
	v_mov_b32_e32 v3, 0
	s_and_saveexec_b64 s[4:5], vcc
	s_cbranch_execz .LBB0_557
	v_add_u32_e32 v0, s33, v8
	v_mad_u64_u32 v[8:9], s[36:37], v0, s11, v[4:5]
	global_load_dwordx4 v[0:3], v[8:9], off offset:1024
	global_load_dwordx4 v[240:243], v[8:9], off
	s_waitcnt vmcnt(1)
	v_lshlrev_b32_e32 v10, 16, v0
	v_and_b32_e32 v11, 0xffff0000, v0
	v_mul_f32_e32 v0, 0xbfb8aa3b, v10
	v_mul_f32_e32 v10, 0xbfb8aa3b, v11
	v_exp_f32_e32 v10, v10
	v_and_b32_e32 v11, 0xffff0000, v1
	v_exp_f32_e32 v0, v0
	v_add_f32_e32 v10, 1.0, v10
	v_rcp_f32_e32 v12, v10
	v_lshlrev_b32_e32 v10, 16, v1
	v_mul_f32_e32 v1, 0xbfb8aa3b, v10
	v_mul_f32_e32 v10, 0xbfb8aa3b, v11
	v_exp_f32_e32 v10, v10
	v_exp_f32_e32 v1, v1
	v_add_f32_e32 v0, 1.0, v0
	v_rcp_f32_e32 v0, v0
	v_add_f32_e32 v10, 1.0, v10
	v_rcp_f32_e32 v13, v10
	v_add_f32_e32 v1, 1.0, v1
	v_rcp_f32_e32 v1, v1
	s_waitcnt vmcnt(0)
	v_mov_b32_e32 v8, v240
	v_mov_b32_e32 v9, v241
	v_mov_b32_e32 v10, v242
	v_mov_b32_e32 v11, v243
	v_lshlrev_b32_e32 v15, 16, v9
	v_lshlrev_b32_e32 v14, 16, v8
	v_and_b32_e32 v9, 0xffff0000, v9
	v_and_b32_e32 v8, 0xffff0000, v8
	v_pk_mul_f32 v[0:1], v[0:1], v[14:15]
	v_pk_mul_f32 v[8:9], v[12:13], v[8:9]
	v_and_b32_sdwa v12, v1, v198 dst_sel:DWORD dst_unused:UNUSED_PAD src0_sel:WORD_1 src1_sel:DWORD
	v_and_b32_sdwa v13, v0, v198 dst_sel:DWORD dst_unused:UNUSED_PAD src0_sel:WORD_1 src1_sel:DWORD
	v_add3_u32 v0, v0, v13, s25
	v_add3_u32 v1, v1, v12, s25
	v_and_b32_sdwa v12, v9, v198 dst_sel:DWORD dst_unused:UNUSED_PAD src0_sel:WORD_1 src1_sel:DWORD
	v_and_b32_sdwa v13, v8, v198 dst_sel:DWORD dst_unused:UNUSED_PAD src0_sel:WORD_1 src1_sel:DWORD
	v_add3_u32 v9, v9, v12, s25
	v_add3_u32 v8, v8, v13, s25
	v_and_b32_e32 v9, 0xffff0000, v9
	v_and_b32_e32 v8, 0xffff0000, v8
	v_or_b32_sdwa v1, v9, v1 dst_sel:DWORD dst_unused:UNUSED_PAD src0_sel:DWORD src1_sel:WORD_1
	v_or_b32_sdwa v0, v8, v0 dst_sel:DWORD dst_unused:UNUSED_PAD src0_sel:DWORD src1_sel:WORD_1
	v_lshlrev_b32_e32 v8, 16, v2
	v_and_b32_e32 v9, 0xffff0000, v2
	v_mul_f32_e32 v2, 0xbfb8aa3b, v8
	v_mul_f32_e32 v8, 0xbfb8aa3b, v9
	v_lshlrev_b32_e32 v9, 16, v3
	v_and_b32_e32 v12, 0xffff0000, v3
	v_mul_f32_e32 v3, 0xbfb8aa3b, v9
	v_exp_f32_e32 v2, v2
	v_exp_f32_e32 v3, v3
	v_mul_f32_e32 v9, 0xbfb8aa3b, v12
	v_exp_f32_e32 v8, v8
	v_exp_f32_e32 v9, v9
	v_add_f32_e32 v2, 1.0, v2
	v_add_f32_e32 v3, 1.0, v3
	v_rcp_f32_e32 v2, v2
	v_add_f32_e32 v8, 1.0, v8
	v_rcp_f32_e32 v3, v3
	v_add_f32_e32 v9, 1.0, v9
	v_rcp_f32_e32 v8, v8
	v_rcp_f32_e32 v9, v9
	v_lshlrev_b32_e32 v13, 16, v11
	v_lshlrev_b32_e32 v12, 16, v10
	v_and_b32_e32 v11, 0xffff0000, v11
	v_and_b32_e32 v10, 0xffff0000, v10
	v_pk_mul_f32 v[2:3], v[2:3], v[12:13]
	v_pk_mul_f32 v[8:9], v[8:9], v[10:11]
	v_and_b32_sdwa v10, v3, v198 dst_sel:DWORD dst_unused:UNUSED_PAD src0_sel:WORD_1 src1_sel:DWORD
	v_and_b32_sdwa v11, v2, v198 dst_sel:DWORD dst_unused:UNUSED_PAD src0_sel:WORD_1 src1_sel:DWORD
	v_add3_u32 v2, v2, v11, s25
	v_add3_u32 v3, v3, v10, s25
	v_and_b32_sdwa v10, v9, v198 dst_sel:DWORD dst_unused:UNUSED_PAD src0_sel:WORD_1 src1_sel:DWORD
	v_and_b32_sdwa v11, v8, v198 dst_sel:DWORD dst_unused:UNUSED_PAD src0_sel:WORD_1 src1_sel:DWORD
	v_add3_u32 v9, v9, v10, s25
	v_add3_u32 v8, v8, v11, s25
	v_and_b32_e32 v9, 0xffff0000, v9
	v_and_b32_e32 v8, 0xffff0000, v8
	v_or_b32_sdwa v3, v9, v3 dst_sel:DWORD dst_unused:UNUSED_PAD src0_sel:DWORD src1_sel:WORD_1
	v_or_b32_sdwa v2, v8, v2 dst_sel:DWORD dst_unused:UNUSED_PAD src0_sel:DWORD src1_sel:WORD_1
	s_branch .LBB0_557
